# hand-written mode-5 indexer sweep loop (pk clamp relu, scaled domain, med3 bucket)
# speedup vs baseline: 1.0191x; 1.0191x over previous
; __device__ __forceinline__ int bucketf(float f) { const unsigned u = __float_as_uint(f); const int idx = (int)((u >> 20) & 0x7FFu); const int c = min(max(idx - 816, 128), 255); return c ^ (((int)u >> 31) & 255); }
;     ...
;     const int kt0 = wid >> 1; const int nit = kt0 <= c ? 2 * ((c - kt0) / 4 + 1) : 0;
;     const float t_lo = bucket_lo((int)pref), t_hi = bucket_lo((int)pref + 1);
;     const bf16_t* ikp = Zb + (size_t)(64 * kt0 + r32) * NZ + ZIK + hi * 8;
;     bf16x8 a0, a1;
;     if (nit > 0) { a0 = *(const bf16x8*)ikp; a1 = *(const bf16x8*)(ikp + 16); }
; #pragma unroll 1
;     for (int it = 0; it < nit; ++it) {
;         const int kt = kt0 + 4 * (it >> 1), kb = it & 1;
;         const int itn = it + 1 < nit ? it + 1 : it;
;         const bf16_t* np = ikp + (size_t)(256 * (itn >> 1) + 32 * (itn & 1)) * NZ; const bf16x8 n0 = *(const bf16x8*)np, n1 = *(const bf16x8*)(np + 16);
;         f32x2v sc2[8];
; #pragma unroll
;         for (int r = 0; r < 8; ++r) sc2[r] = (f32x2v){0.f, 0.f};
;     ...
;         { f32x16 zero16;
; #pragma unroll
;           for (int r = 0; r < 16; ++r) zero16[r] = 0.f;
;           f32x16 dA0, dA1, dB0, dB1; float wA0, wA1, wB0, wB1;
;           SW_MF(0, dA0, dA1, wA0, wA1);
;           SW_MF(1, dB0, dB1, wB0, wB1); __builtin_amdgcn_sched_barrier(0);
;           SW_VA(dA0, dA1, wA0, wA1);    __builtin_amdgcn_sched_barrier(0);
;           SW_MF(2, dA0, dA1, wA0, wA1); __builtin_amdgcn_sched_barrier(0);
;           SW_VA(dB0, dB1, wB0, wB1);    __builtin_amdgcn_sched_barrier(0);
;           SW_MF(3, dB0, dB1, wB0, wB1); __builtin_amdgcn_sched_barrier(0);
;           SW_VA(dA0, dA1, wA0, wA1);    __builtin_amdgcn_sched_barrier(0);
;           SW_VA(dB0, dB1, wB0, wB1); }
;     ...
;         f32x16 sc;
; #pragma unroll
;         for (int r = 0; r < 16; ++r) sc[r] = sc2[r >> 1][r & 1];
;         const unsigned s0 = (unsigned)(64 * kt + 32 * kb + 4 * hi);
; #pragma unroll
;         for (int r = 0; r < 16; ++r) { const unsigned s = s0 + (unsigned)((r & 3) + 8 * (r >> 2));
;             if (MODE == 5) { __hip_atomic_fetch_add(hist + 64 * bucketf(sc[r]), 1u, __ATOMIC_RELAXED, __HIP_MEMORY_SCOPE_WORKGROUP); continue; }
.LBB0_979:
	v_add_u32_e32 v1, 0x200, v1
	v_cmp_lt_u32_e32 vcc, s62, v1
	ds_write_b32 v0, v155
	s_or_b64 s[0:1], vcc, s[0:1]
	v_add_u32_e32 v0, 0x800, v0
	s_andn2_b64 exec, exec, s[0:1]
	s_cbranch_execnz .LBB0_979
	s_or_b64 exec, exec, s[0:1]
	s_lshr_b32 s24, s3, 7
	v_mov_b32_e32 v0, s24
	v_sub_co_u32_e64 v0, s[18:19], s2, v0
	s_lshl_b32 s0, s69, 5
	v_readfirstlane_b32 s1, v0
	v_lshl_or_b32 v2, s24, 6, v151
	v_mov_b64_e32 v[0:1], s[36:37]
	v_and_or_b32 v169, s0, 32, v151
	s_lshr_b32 s1, s1, 1
	v_mad_u64_u32 v[0:1], s[2:3], v2, s61, v[0:1]
	v_lshlrev_b32_e32 v154, 1, v152
	v_lshlrev_b32_e32 v171, 2, v169
	s_and_b32 s25, s1, 0x7ffffffe
	v_lshl_add_u64 v[0:1], v[0:1], 0, v[154:155]
	s_mov_b64 s[2:3], 0x1300
	v_add_u32_e32 v230, 0x100, v171
	v_mad_u32_u24 v165, v169, s86, v199
	v_add_u32_e32 v167, s51, v171
	s_add_i32 s25, s25, 2
	v_lshl_add_u64 v[140:141], v[0:1], 0, s[2:3]
	s_and_b64 vcc, exec, s[18:19]
	s_waitcnt lgkmcnt(0)
	s_barrier
	s_cbranch_vccnz .LBB0_983
	global_load_dwordx4 v[76:79], v[140:141], off
	global_load_dwordx4 v[72:75], v[140:141], off offset:32
	s_mov_b32 s2, 0
	v_mov_b32_e32 v112, 0x2c800000
	v_mov_b32_e32 v113, 0x2c800000
	v_mov_b32_e32 v117, 0x280
	v_mov_b32_e32 v118, 0x2ff
	v_add_u32_e32 v116, 0xfffe0000, v230
.Lm5_loop:
	s_add_i32 s1, s2, 1
	s_cmp_lt_u32 s1, s25
	s_cselect_b32 s3, s1, s2
	s_lshl_b32 vcc_lo, s3, 7
	s_and_b32 vcc_lo, vcc_lo, 0x7fffff00
	s_lshl_b32 s3, s3, 5
	s_and_b32 s3, s3, 32
	s_or_b32 s3, vcc_lo, s3
	ds_read_b128 v[0:3], v165
	ds_read_b128 v[4:7], v165 offset:32
	ds_read_b128 v[8:11], v165 offset:64
	ds_read_b128 v[12:15], v165 offset:96
	ds_read2st64_b32 v[80:81], v167 offset1:1
	ds_read2st64_b32 v[82:83], v167 offset0:2 offset1:3
	ds_read2st64_b32 v[84:85], v167 offset0:4 offset1:5
	ds_read2st64_b32 v[86:87], v167 offset0:6 offset1:7
	v_mad_u64_u32 v[114:115], vcc, s3, v223, v[140:141]
	s_nop 0
	global_load_dwordx4 v[64:67], v[114:115], off
	global_load_dwordx4 v[68:71], v[114:115], off offset:32
	s_waitcnt vmcnt(2) lgkmcnt(6)
	v_mfma_f32_32x32x16_bf16 v[16:31], v[76:79], v[0:3], 0
	v_mfma_f32_32x32x16_bf16 v[16:31], v[72:75], v[4:7], v[16:31]
	ds_read_b128 v[0:3], v165 offset:128
	ds_read_b128 v[4:7], v165 offset:160
	s_waitcnt lgkmcnt(6)
	v_mfma_f32_32x32x16_bf16 v[32:47], v[76:79], v[8:11], 0
	v_mfma_f32_32x32x16_bf16 v[32:47], v[72:75], v[12:15], v[32:47]
	ds_read_b128 v[8:11], v165 offset:192
	ds_read_b128 v[12:15], v165 offset:224
	s_nop 7
	s_waitcnt lgkmcnt(4)
	v_mov_b32_e32 v104, v81
	v_mov_b32_e32 v106, v83
	v_mov_b32_e32 v108, v85
	v_mov_b32_e32 v110, v87
	v_pk_mul_f32 v[16:17], v[16:17], v[112:113] clamp
	v_pk_mul_f32 v[18:19], v[18:19], v[112:113] clamp
	v_pk_mul_f32 v[20:21], v[20:21], v[112:113] clamp
	v_pk_mul_f32 v[22:23], v[22:23], v[112:113] clamp
	v_pk_mul_f32 v[24:25], v[24:25], v[112:113] clamp
	v_pk_mul_f32 v[26:27], v[26:27], v[112:113] clamp
	v_pk_mul_f32 v[28:29], v[28:29], v[112:113] clamp
	v_pk_mul_f32 v[30:31], v[30:31], v[112:113] clamp
	v_pk_fma_f32 v[88:89], v[16:17], v[80:81], 0 op_sel_hi:[1,0,0]
	v_pk_fma_f32 v[90:91], v[18:19], v[80:81], 0 op_sel_hi:[1,0,0]
	v_pk_fma_f32 v[92:93], v[20:21], v[80:81], 0 op_sel_hi:[1,0,0]
	v_pk_fma_f32 v[94:95], v[22:23], v[80:81], 0 op_sel_hi:[1,0,0]
	v_pk_fma_f32 v[96:97], v[24:25], v[80:81], 0 op_sel_hi:[1,0,0]
	v_pk_fma_f32 v[98:99], v[26:27], v[80:81], 0 op_sel_hi:[1,0,0]
	v_pk_fma_f32 v[100:101], v[28:29], v[80:81], 0 op_sel_hi:[1,0,0]
	v_pk_fma_f32 v[102:103], v[30:31], v[80:81], 0 op_sel_hi:[1,0,0]
	s_waitcnt lgkmcnt(2)
	v_mfma_f32_32x32x16_bf16 v[16:31], v[76:79], v[0:3], 0
	v_mfma_f32_32x32x16_bf16 v[16:31], v[72:75], v[4:7], v[16:31]
	ds_read_b128 v[0:3], v165 offset:256
	ds_read_b128 v[4:7], v165 offset:288
	v_pk_mul_f32 v[32:33], v[32:33], v[112:113] clamp
	v_pk_mul_f32 v[34:35], v[34:35], v[112:113] clamp
	v_pk_mul_f32 v[36:37], v[36:37], v[112:113] clamp
	v_pk_mul_f32 v[38:39], v[38:39], v[112:113] clamp
	v_pk_mul_f32 v[40:41], v[40:41], v[112:113] clamp
	v_pk_mul_f32 v[42:43], v[42:43], v[112:113] clamp
	v_pk_mul_f32 v[44:45], v[44:45], v[112:113] clamp
	v_pk_mul_f32 v[46:47], v[46:47], v[112:113] clamp
	v_pk_fma_f32 v[88:89], v[32:33], v[104:105], v[88:89] op_sel_hi:[1,0,1]
	v_pk_fma_f32 v[90:91], v[34:35], v[104:105], v[90:91] op_sel_hi:[1,0,1]
	v_pk_fma_f32 v[92:93], v[36:37], v[104:105], v[92:93] op_sel_hi:[1,0,1]
	v_pk_fma_f32 v[94:95], v[38:39], v[104:105], v[94:95] op_sel_hi:[1,0,1]
	v_pk_fma_f32 v[96:97], v[40:41], v[104:105], v[96:97] op_sel_hi:[1,0,1]
	v_pk_fma_f32 v[98:99], v[42:43], v[104:105], v[98:99] op_sel_hi:[1,0,1]
	v_pk_fma_f32 v[100:101], v[44:45], v[104:105], v[100:101] op_sel_hi:[1,0,1]
	v_pk_fma_f32 v[102:103], v[46:47], v[104:105], v[102:103] op_sel_hi:[1,0,1]
	s_waitcnt lgkmcnt(2)
	v_mfma_f32_32x32x16_bf16 v[32:47], v[76:79], v[8:11], 0
	v_mfma_f32_32x32x16_bf16 v[32:47], v[72:75], v[12:15], v[32:47]
	ds_read_b128 v[8:11], v165 offset:320
	ds_read_b128 v[12:15], v165 offset:352
	v_pk_mul_f32 v[16:17], v[16:17], v[112:113] clamp
	v_pk_mul_f32 v[18:19], v[18:19], v[112:113] clamp
	v_pk_mul_f32 v[20:21], v[20:21], v[112:113] clamp
	v_pk_mul_f32 v[22:23], v[22:23], v[112:113] clamp
	v_pk_mul_f32 v[24:25], v[24:25], v[112:113] clamp
	v_pk_mul_f32 v[26:27], v[26:27], v[112:113] clamp
	v_pk_mul_f32 v[28:29], v[28:29], v[112:113] clamp
	v_pk_mul_f32 v[30:31], v[30:31], v[112:113] clamp
	v_pk_fma_f32 v[88:89], v[16:17], v[82:83], v[88:89] op_sel_hi:[1,0,1]
	v_pk_fma_f32 v[90:91], v[18:19], v[82:83], v[90:91] op_sel_hi:[1,0,1]
	v_pk_fma_f32 v[92:93], v[20:21], v[82:83], v[92:93] op_sel_hi:[1,0,1]
	v_pk_fma_f32 v[94:95], v[22:23], v[82:83], v[94:95] op_sel_hi:[1,0,1]
	v_pk_fma_f32 v[96:97], v[24:25], v[82:83], v[96:97] op_sel_hi:[1,0,1]
	v_pk_fma_f32 v[98:99], v[26:27], v[82:83], v[98:99] op_sel_hi:[1,0,1]
	v_pk_fma_f32 v[100:101], v[28:29], v[82:83], v[100:101] op_sel_hi:[1,0,1]
	v_pk_fma_f32 v[102:103], v[30:31], v[82:83], v[102:103] op_sel_hi:[1,0,1]
	s_waitcnt lgkmcnt(2)
;     ...
;         { f32x16 zero16;
; #pragma unroll
;           for (int r = 0; r < 16; ++r) zero16[r] = 0.f;
;           f32x16 dA0, dA1, dB0, dB1; float wA0, wA1, wB0, wB1;
;           SW_MF(0, dA0, dA1, wA0, wA1);
;           SW_MF(1, dB0, dB1, wB0, wB1); __builtin_amdgcn_sched_barrier(0);
;           SW_VA(dA0, dA1, wA0, wA1);    __builtin_amdgcn_sched_barrier(0);
;           SW_MF(2, dA0, dA1, wA0, wA1); __builtin_amdgcn_sched_barrier(0);
;           SW_VA(dB0, dB1, wB0, wB1);    __builtin_amdgcn_sched_barrier(0);
;           SW_MF(3, dB0, dB1, wB0, wB1); __builtin_amdgcn_sched_barrier(0);
;           SW_VA(dA0, dA1, wA0, wA1);    __builtin_amdgcn_sched_barrier(0);
;           SW_VA(dB0, dB1, wB0, wB1); }
	v_mfma_f32_32x32x16_bf16 v[16:31], v[76:79], v[0:3], 0
	v_mfma_f32_32x32x16_bf16 v[16:31], v[72:75], v[4:7], v[16:31]
	ds_read_b128 v[0:3], v165 offset:384
	ds_read_b128 v[4:7], v165 offset:416
	v_pk_mul_f32 v[32:33], v[32:33], v[112:113] clamp
	v_pk_mul_f32 v[34:35], v[34:35], v[112:113] clamp
	v_pk_mul_f32 v[36:37], v[36:37], v[112:113] clamp
	v_pk_mul_f32 v[38:39], v[38:39], v[112:113] clamp
	v_pk_mul_f32 v[40:41], v[40:41], v[112:113] clamp
	v_pk_mul_f32 v[42:43], v[42:43], v[112:113] clamp
	v_pk_mul_f32 v[44:45], v[44:45], v[112:113] clamp
	v_pk_mul_f32 v[46:47], v[46:47], v[112:113] clamp
	v_pk_fma_f32 v[88:89], v[32:33], v[106:107], v[88:89] op_sel_hi:[1,0,1]
	v_pk_fma_f32 v[90:91], v[34:35], v[106:107], v[90:91] op_sel_hi:[1,0,1]
	v_pk_fma_f32 v[92:93], v[36:37], v[106:107], v[92:93] op_sel_hi:[1,0,1]
	v_pk_fma_f32 v[94:95], v[38:39], v[106:107], v[94:95] op_sel_hi:[1,0,1]
	v_pk_fma_f32 v[96:97], v[40:41], v[106:107], v[96:97] op_sel_hi:[1,0,1]
	v_pk_fma_f32 v[98:99], v[42:43], v[106:107], v[98:99] op_sel_hi:[1,0,1]
	v_pk_fma_f32 v[100:101], v[44:45], v[106:107], v[100:101] op_sel_hi:[1,0,1]
	v_pk_fma_f32 v[102:103], v[46:47], v[106:107], v[102:103] op_sel_hi:[1,0,1]
	s_waitcnt lgkmcnt(2)
	v_mfma_f32_32x32x16_bf16 v[32:47], v[76:79], v[8:11], 0
	v_mfma_f32_32x32x16_bf16 v[32:47], v[72:75], v[12:15], v[32:47]
	ds_read_b128 v[8:11], v165 offset:448
	ds_read_b128 v[12:15], v165 offset:480
	v_pk_mul_f32 v[16:17], v[16:17], v[112:113] clamp
	v_pk_mul_f32 v[18:19], v[18:19], v[112:113] clamp
	v_pk_mul_f32 v[20:21], v[20:21], v[112:113] clamp
	v_pk_mul_f32 v[22:23], v[22:23], v[112:113] clamp
	v_pk_mul_f32 v[24:25], v[24:25], v[112:113] clamp
	v_pk_mul_f32 v[26:27], v[26:27], v[112:113] clamp
	v_pk_mul_f32 v[28:29], v[28:29], v[112:113] clamp
	v_pk_mul_f32 v[30:31], v[30:31], v[112:113] clamp
	v_pk_fma_f32 v[88:89], v[16:17], v[84:85], v[88:89] op_sel_hi:[1,0,1]
	v_pk_fma_f32 v[90:91], v[18:19], v[84:85], v[90:91] op_sel_hi:[1,0,1]
	v_pk_fma_f32 v[92:93], v[20:21], v[84:85], v[92:93] op_sel_hi:[1,0,1]
	v_pk_fma_f32 v[94:95], v[22:23], v[84:85], v[94:95] op_sel_hi:[1,0,1]
	v_pk_fma_f32 v[96:97], v[24:25], v[84:85], v[96:97] op_sel_hi:[1,0,1]
	v_pk_fma_f32 v[98:99], v[26:27], v[84:85], v[98:99] op_sel_hi:[1,0,1]
	v_pk_fma_f32 v[100:101], v[28:29], v[84:85], v[100:101] op_sel_hi:[1,0,1]
	v_pk_fma_f32 v[102:103], v[30:31], v[84:85], v[102:103] op_sel_hi:[1,0,1]
	s_waitcnt lgkmcnt(2)
	v_mfma_f32_32x32x16_bf16 v[16:31], v[76:79], v[0:3], 0
	v_mfma_f32_32x32x16_bf16 v[16:31], v[72:75], v[4:7], v[16:31]
	v_pk_mul_f32 v[32:33], v[32:33], v[112:113] clamp
	v_pk_mul_f32 v[34:35], v[34:35], v[112:113] clamp
	v_pk_mul_f32 v[36:37], v[36:37], v[112:113] clamp
	v_pk_mul_f32 v[38:39], v[38:39], v[112:113] clamp
	v_pk_mul_f32 v[40:41], v[40:41], v[112:113] clamp
	v_pk_mul_f32 v[42:43], v[42:43], v[112:113] clamp
	v_pk_mul_f32 v[44:45], v[44:45], v[112:113] clamp
	v_pk_mul_f32 v[46:47], v[46:47], v[112:113] clamp
	v_pk_fma_f32 v[88:89], v[32:33], v[108:109], v[88:89] op_sel_hi:[1,0,1]
	v_pk_fma_f32 v[90:91], v[34:35], v[108:109], v[90:91] op_sel_hi:[1,0,1]
	v_pk_fma_f32 v[92:93], v[36:37], v[108:109], v[92:93] op_sel_hi:[1,0,1]
	v_pk_fma_f32 v[94:95], v[38:39], v[108:109], v[94:95] op_sel_hi:[1,0,1]
	v_pk_fma_f32 v[96:97], v[40:41], v[108:109], v[96:97] op_sel_hi:[1,0,1]
	v_pk_fma_f32 v[98:99], v[42:43], v[108:109], v[98:99] op_sel_hi:[1,0,1]
	v_pk_fma_f32 v[100:101], v[44:45], v[108:109], v[100:101] op_sel_hi:[1,0,1]
	v_pk_fma_f32 v[102:103], v[46:47], v[108:109], v[102:103] op_sel_hi:[1,0,1]
	s_waitcnt lgkmcnt(0)
; __device__ __forceinline__ int bucketf(float f) { const unsigned u = __float_as_uint(f); const int idx = (int)((u >> 20) & 0x7FFu); const int c = min(max(idx - 816, 128), 255); return c ^ (((int)u >> 31) & 255); }
;     ...
;         { f32x16 zero16;
; #pragma unroll
;           for (int r = 0; r < 16; ++r) zero16[r] = 0.f;
;           f32x16 dA0, dA1, dB0, dB1; float wA0, wA1, wB0, wB1;
;           SW_MF(0, dA0, dA1, wA0, wA1);
;           SW_MF(1, dB0, dB1, wB0, wB1); __builtin_amdgcn_sched_barrier(0);
;           SW_VA(dA0, dA1, wA0, wA1);    __builtin_amdgcn_sched_barrier(0);
;           SW_MF(2, dA0, dA1, wA0, wA1); __builtin_amdgcn_sched_barrier(0);
;           SW_VA(dB0, dB1, wB0, wB1);    __builtin_amdgcn_sched_barrier(0);
;           SW_MF(3, dB0, dB1, wB0, wB1); __builtin_amdgcn_sched_barrier(0);
;           SW_VA(dA0, dA1, wA0, wA1);    __builtin_amdgcn_sched_barrier(0);
;           SW_VA(dB0, dB1, wB0, wB1); }
;     ...
;         f32x16 sc;
; #pragma unroll
;         for (int r = 0; r < 16; ++r) sc[r] = sc2[r >> 1][r & 1];
;         const unsigned s0 = (unsigned)(64 * kt + 32 * kb + 4 * hi);
; #pragma unroll
;         for (int r = 0; r < 16; ++r) { const unsigned s = s0 + (unsigned)((r & 3) + 8 * (r >> 2));
;             if (MODE == 5) { __hip_atomic_fetch_add(hist + 64 * bucketf(sc[r]), 1u, __ATOMIC_RELAXED, __HIP_MEMORY_SCOPE_WORKGROUP); continue; }
	v_mfma_f32_32x32x16_bf16 v[32:47], v[76:79], v[8:11], 0
	v_mfma_f32_32x32x16_bf16 v[32:47], v[72:75], v[12:15], v[32:47]
	v_pk_mul_f32 v[16:17], v[16:17], v[112:113] clamp
	v_pk_mul_f32 v[18:19], v[18:19], v[112:113] clamp
	v_pk_mul_f32 v[20:21], v[20:21], v[112:113] clamp
	v_pk_mul_f32 v[22:23], v[22:23], v[112:113] clamp
	v_pk_mul_f32 v[24:25], v[24:25], v[112:113] clamp
	v_pk_mul_f32 v[26:27], v[26:27], v[112:113] clamp
	v_pk_mul_f32 v[28:29], v[28:29], v[112:113] clamp
	v_pk_mul_f32 v[30:31], v[30:31], v[112:113] clamp
	v_pk_fma_f32 v[88:89], v[16:17], v[86:87], v[88:89] op_sel_hi:[1,0,1]
	v_pk_fma_f32 v[90:91], v[18:19], v[86:87], v[90:91] op_sel_hi:[1,0,1]
	v_pk_fma_f32 v[92:93], v[20:21], v[86:87], v[92:93] op_sel_hi:[1,0,1]
	v_pk_fma_f32 v[94:95], v[22:23], v[86:87], v[94:95] op_sel_hi:[1,0,1]
	v_pk_fma_f32 v[96:97], v[24:25], v[86:87], v[96:97] op_sel_hi:[1,0,1]
	v_pk_fma_f32 v[98:99], v[26:27], v[86:87], v[98:99] op_sel_hi:[1,0,1]
	v_pk_fma_f32 v[100:101], v[28:29], v[86:87], v[100:101] op_sel_hi:[1,0,1]
	v_pk_fma_f32 v[102:103], v[30:31], v[86:87], v[102:103] op_sel_hi:[1,0,1]
	v_pk_mul_f32 v[32:33], v[32:33], v[112:113] clamp
	v_pk_mul_f32 v[34:35], v[34:35], v[112:113] clamp
	v_pk_mul_f32 v[36:37], v[36:37], v[112:113] clamp
	v_pk_mul_f32 v[38:39], v[38:39], v[112:113] clamp
	v_pk_mul_f32 v[40:41], v[40:41], v[112:113] clamp
	v_pk_mul_f32 v[42:43], v[42:43], v[112:113] clamp
	v_pk_mul_f32 v[44:45], v[44:45], v[112:113] clamp
	v_pk_mul_f32 v[46:47], v[46:47], v[112:113] clamp
	v_pk_fma_f32 v[88:89], v[32:33], v[110:111], v[88:89] op_sel_hi:[1,0,1]
	v_pk_fma_f32 v[90:91], v[34:35], v[110:111], v[90:91] op_sel_hi:[1,0,1]
	v_pk_fma_f32 v[92:93], v[36:37], v[110:111], v[92:93] op_sel_hi:[1,0,1]
	v_pk_fma_f32 v[94:95], v[38:39], v[110:111], v[94:95] op_sel_hi:[1,0,1]
	v_pk_fma_f32 v[96:97], v[40:41], v[110:111], v[96:97] op_sel_hi:[1,0,1]
	v_pk_fma_f32 v[98:99], v[42:43], v[110:111], v[98:99] op_sel_hi:[1,0,1]
	v_pk_fma_f32 v[100:101], v[44:45], v[110:111], v[100:101] op_sel_hi:[1,0,1]
	v_pk_fma_f32 v[102:103], v[46:47], v[110:111], v[102:103] op_sel_hi:[1,0,1]
	v_bfe_u32 v48, v88, 20, 11
	v_ashrrev_i32_e32 v49, 31, v88
	v_med3_u32 v48, v48, v117, v118
	v_bitop3_b32 v48, v48, v49, s56 bitop3:0x78
	v_lshl_add_u32 v48, v48, 8, v116
	ds_add_u32 v48, v222
	v_bfe_u32 v50, v89, 20, 11
	v_ashrrev_i32_e32 v51, 31, v89
	v_med3_u32 v50, v50, v117, v118
	v_bitop3_b32 v50, v50, v51, s56 bitop3:0x78
	v_lshl_add_u32 v50, v50, 8, v116
	ds_add_u32 v50, v222
	v_bfe_u32 v52, v90, 20, 11
	v_ashrrev_i32_e32 v53, 31, v90
	v_med3_u32 v52, v52, v117, v118
	v_bitop3_b32 v52, v52, v53, s56 bitop3:0x78
	v_lshl_add_u32 v52, v52, 8, v116
	ds_add_u32 v52, v222
	v_bfe_u32 v54, v91, 20, 11
	v_ashrrev_i32_e32 v55, 31, v91
	v_med3_u32 v54, v54, v117, v118
	v_bitop3_b32 v54, v54, v55, s56 bitop3:0x78
	v_lshl_add_u32 v54, v54, 8, v116
	ds_add_u32 v54, v222
	v_bfe_u32 v48, v92, 20, 11
	v_ashrrev_i32_e32 v49, 31, v92
	v_med3_u32 v48, v48, v117, v118
	v_bitop3_b32 v48, v48, v49, s56 bitop3:0x78
	v_lshl_add_u32 v48, v48, 8, v116
	ds_add_u32 v48, v222
	v_bfe_u32 v50, v93, 20, 11
	v_ashrrev_i32_e32 v51, 31, v93
	v_med3_u32 v50, v50, v117, v118
	v_bitop3_b32 v50, v50, v51, s56 bitop3:0x78
	v_lshl_add_u32 v50, v50, 8, v116
	ds_add_u32 v50, v222
	v_bfe_u32 v52, v94, 20, 11
	v_ashrrev_i32_e32 v53, 31, v94
	v_med3_u32 v52, v52, v117, v118
	v_bitop3_b32 v52, v52, v53, s56 bitop3:0x78
	v_lshl_add_u32 v52, v52, 8, v116
	ds_add_u32 v52, v222
	v_bfe_u32 v54, v95, 20, 11
	v_ashrrev_i32_e32 v55, 31, v95
	v_med3_u32 v54, v54, v117, v118
	v_bitop3_b32 v54, v54, v55, s56 bitop3:0x78
	v_lshl_add_u32 v54, v54, 8, v116
	ds_add_u32 v54, v222
	v_bfe_u32 v48, v96, 20, 11
	v_ashrrev_i32_e32 v49, 31, v96
	v_med3_u32 v48, v48, v117, v118
	v_bitop3_b32 v48, v48, v49, s56 bitop3:0x78
	v_lshl_add_u32 v48, v48, 8, v116
	ds_add_u32 v48, v222
	v_bfe_u32 v50, v97, 20, 11
	v_ashrrev_i32_e32 v51, 31, v97
	v_med3_u32 v50, v50, v117, v118
	v_bitop3_b32 v50, v50, v51, s56 bitop3:0x78
	v_lshl_add_u32 v50, v50, 8, v116
	ds_add_u32 v50, v222
	v_bfe_u32 v52, v98, 20, 11
	v_ashrrev_i32_e32 v53, 31, v98
	v_med3_u32 v52, v52, v117, v118
	v_bitop3_b32 v52, v52, v53, s56 bitop3:0x78
	v_lshl_add_u32 v52, v52, 8, v116
	ds_add_u32 v52, v222
	v_bfe_u32 v54, v99, 20, 11
	v_ashrrev_i32_e32 v55, 31, v99
	v_med3_u32 v54, v54, v117, v118
	v_bitop3_b32 v54, v54, v55, s56 bitop3:0x78
	v_lshl_add_u32 v54, v54, 8, v116
	ds_add_u32 v54, v222
	v_bfe_u32 v48, v100, 20, 11
	v_ashrrev_i32_e32 v49, 31, v100
	v_med3_u32 v48, v48, v117, v118
	v_bitop3_b32 v48, v48, v49, s56 bitop3:0x78
	v_lshl_add_u32 v48, v48, 8, v116
	ds_add_u32 v48, v222
	v_bfe_u32 v50, v101, 20, 11
	v_ashrrev_i32_e32 v51, 31, v101
	v_med3_u32 v50, v50, v117, v118
	v_bitop3_b32 v50, v50, v51, s56 bitop3:0x78
	v_lshl_add_u32 v50, v50, 8, v116
	ds_add_u32 v50, v222
	v_bfe_u32 v52, v102, 20, 11
	v_ashrrev_i32_e32 v53, 31, v102
	v_med3_u32 v52, v52, v117, v118
	v_bitop3_b32 v52, v52, v53, s56 bitop3:0x78
	v_lshl_add_u32 v52, v52, 8, v116
	ds_add_u32 v52, v222
	v_bfe_u32 v54, v103, 20, 11
	v_ashrrev_i32_e32 v55, 31, v103
	v_med3_u32 v54, v54, v117, v118
	v_bitop3_b32 v54, v54, v55, s56 bitop3:0x78
	v_lshl_add_u32 v54, v54, 8, v116
	ds_add_u32 v54, v222
	s_waitcnt vmcnt(0)
	v_mov_b64_e32 v[76:77], v[64:65]
	v_mov_b64_e32 v[78:79], v[66:67]
	v_mov_b64_e32 v[72:73], v[68:69]
	v_mov_b64_e32 v[74:75], v[70:71]
	s_cmp_lg_u32 s25, s1
	s_mov_b32 s2, s1
	s_cbranch_scc1 .Lm5_loop
